# early L1 invalidate in grid barriers + down-projection epilogue rewritten as a pipelined stream that skips the dead bf16 copy in the last layer
# baseline (speedup 1.0000x reference)
; DI void st8(bf16_t* p, f32x4 a, f32x4 b) { u32x4 w; w.x = pk2(a[0], a[1]); w.y = pk2(a[2], a[3]); w.z = pk2(b[0], b[1]); w.w = pk2(b[2], b[3]); *(u32x4*)p = w; }
;     DI void operator()(const AccT& acc, const Unit& u, int wr, int wc, int fr, int fq, const LAS float* rt) const {
;         const int col0 = u.pn * BM + wc * 32 + 8 * fq;
;         f32x4 gv[2][2];
; #pragma unroll
;         for (int bj = 0; bj < 2; ++bj) { gv[bj][0] = *(const f32x4*)(gain + col0 + bj * HALF); gv[bj][1] = *(const f32x4*)(gain + col0 + bj * HALF + 4); }
; #pragma unroll
;         for (int ai = 0; ai < 2; ++ai)
; #pragma unroll
;             for (int mh = 0; mh < 2; ++mh) {
;                 f32x4 bx[2][2][2];
; #pragma unroll
;                 for (int mm = 0; mm < 2; ++mm) { const int row = u.pm * BM + ai * HALF + wr * 64 + (mh * 2 + mm) * 16 + fr;
; #pragma unroll
;                     for (int bj = 0; bj < 2; ++bj) { const size_t o = (size_t)row * DM + col0 + bj * HALF; bx[mm][bj][0] = *(const f32x4*)(base + o); bx[mm][bj][1] = *(const f32x4*)(base + o + 4); } }
;                 __builtin_amdgcn_sched_barrier(0);
; #pragma unroll
;                 for (int mm = 0; mm < 2; ++mm) { const int m = mh * 2 + mm; const int row = u.pm * BM + ai * HALF + wr * 64 + m * 16 + fr; float ss = 0.f;
; #pragma unroll
;                     for (int bj = 0; bj < 2; ++bj) { const size_t o = (size_t)row * DM + col0 + bj * HALF;
;                         const f32x4 x0 = bx[mm][bj][0] + acc[ai][bj][m][0], x1 = bx[mm][bj][1] + acc[ai][bj][m][1];
;                         *(f32x4*)(out + o) = x0; *(f32x4*)(out + o + 4) = x1;
;                         ss += (x0[0] * x0[0] + x0[1] * x0[1]) + (x0[2] * x0[2] + x0[3] * x0[3]) + (x1[0] * x1[0] + x1[1] * x1[1]) + (x1[2] * x1[2] + x1[3] * x1[3]);
;                         st8(hb + o, x0 * gv[bj][0], x1 * gv[bj][1]); }
;                     ss += __shfl_xor(ss, 16); ss += __shfl_xor(ss, 32);
;                     if (fq == 0) part[(size_t)row * 16 + u.pn * 4 + wc] = ss; }
.LBB0_1443:
	v_lshl_add_u32 v151, s44, 8, v180
	v_lshl_or_b32 v152, s78, 8, v182
	v_lshl_add_u32 v146, v151, 10, v152
	v_lshlrev_b32_e32 v148, 1, v146
	v_lshlrev_b32_e32 v146, 2, v146
	v_mov_b32_e32 v147, v146
	v_lshlrev_b32_e32 v153, 2, v152
	global_load_dwordx4 v[78:81], v153, s[64:65]
	global_load_dwordx4 v[82:85], v153, s[64:65] offset:16
	global_load_dwordx4 v[94:97], v153, s[64:65] offset:512
	global_load_dwordx4 v[98:101], v153, s[64:65] offset:528
	v_readlane_b32 s100, v253, 36
	global_load_dwordx4 v[154:157], v146, s[30:31]
	global_load_dwordx4 v[158:161], v146, s[30:31] offset:16
	global_load_dwordx4 v[172:175], v146, s[30:31] offset:512
	global_load_dwordx4 v[176:179], v146, s[30:31] offset:528
	v_add_u32_e32 v146, 0x10000, v146
	global_load_dwordx4 v[184:187], v146, s[30:31]
	global_load_dwordx4 v[188:191], v146, s[30:31] offset:16
	global_load_dwordx4 v[192:195], v146, s[30:31] offset:512
	global_load_dwordx4 v[198:201], v146, s[30:31] offset:528
	v_add_u32_e32 v146, 0x10000, v146
	s_waitcnt vmcnt(4)
	v_pk_add_f32 v[142:143], v[142:143], v[154:155]
	v_pk_add_f32 v[144:145], v[144:145], v[156:157]
	v_pk_add_f32 v[138:139], v[138:139], v[158:159]
	v_pk_add_f32 v[140:141], v[140:141], v[160:161]
	v_pk_add_f32 v[134:135], v[134:135], v[172:173]
	v_pk_add_f32 v[136:137], v[136:137], v[174:175]
	v_pk_add_f32 v[130:131], v[130:131], v[176:177]
	v_pk_add_f32 v[132:133], v[132:133], v[178:179]
	global_store_dwordx4 v147, v[142:145], s[48:49]
	global_store_dwordx4 v147, v[138:141], s[48:49] offset:16
	global_store_dwordx4 v147, v[134:137], s[48:49] offset:512
	global_store_dwordx4 v147, v[130:133], s[48:49] offset:528
	v_mul_f32_e32 v149, v142, v142
	v_mul_f32_e32 v150, v143, v143
	v_fmac_f32_e32 v149, v144, v144
	v_fmac_f32_e32 v150, v145, v145
	v_fmac_f32_e32 v149, v138, v138
	v_fmac_f32_e32 v150, v139, v139
	v_fmac_f32_e32 v149, v140, v140
	v_fmac_f32_e32 v150, v141, v141
	v_fmac_f32_e32 v149, v134, v134
	v_fmac_f32_e32 v150, v135, v135
	v_fmac_f32_e32 v149, v136, v136
	v_fmac_f32_e32 v150, v137, v137
	v_fmac_f32_e32 v149, v130, v130
	v_fmac_f32_e32 v150, v131, v131
	v_fmac_f32_e32 v149, v132, v132
	v_fmac_f32_e32 v150, v133, v133
	s_cmp_lg_u32 s100, 0
	s_cbranch_scc1 .Lskiphb_l15_0
	v_pk_mul_f32 v[154:155], v[142:143], v[78:79]
	v_pk_mul_f32 v[156:157], v[144:145], v[80:81]
	v_pk_mul_f32 v[158:159], v[138:139], v[82:83]
	v_pk_mul_f32 v[160:161], v[140:141], v[84:85]
	v_pk_mul_f32 v[172:173], v[134:135], v[94:95]
	v_pk_mul_f32 v[174:175], v[136:137], v[96:97]
	v_pk_mul_f32 v[176:177], v[130:131], v[98:99]
	v_pk_mul_f32 v[178:179], v[132:133], v[100:101]
	v_cvt_pk_bf16_f32 v154, v154, v155
	v_cvt_pk_bf16_f32 v155, v156, v157
	v_cvt_pk_bf16_f32 v156, v158, v159
	v_cvt_pk_bf16_f32 v157, v160, v161
	v_cvt_pk_bf16_f32 v172, v172, v173
	v_cvt_pk_bf16_f32 v173, v174, v175
	v_cvt_pk_bf16_f32 v174, v176, v177
	v_cvt_pk_bf16_f32 v175, v178, v179
	global_store_dwordx4 v148, v[154:157], s[62:63]
	global_store_dwordx4 v148, v[172:175], s[62:63] offset:256
.Lskiphb_l15_0:
	v_add_f32_e32 v142, v149, v150
	v_add_u32_e32 v147, 0x10000, v147
	v_add_u32_e32 v148, 0x8000, v148
	global_load_dwordx4 v[204:207], v146, s[30:31]
	global_load_dwordx4 v[208:211], v146, s[30:31] offset:16
	global_load_dwordx4 v[158:161], v146, s[30:31] offset:512
	global_load_dwordx4 v[176:179], v146, s[30:31] offset:528
	v_add_u32_e32 v146, 0x10000, v146
	global_load_dwordx4 v[138:141], v146, s[30:31]
	global_load_dwordx4 v[134:137], v146, s[30:31] offset:16
	global_load_dwordx4 v[130:133], v146, s[30:31] offset:512
	global_load_dwordx4 v[154:157], v146, s[30:31] offset:528
	v_add_u32_e32 v146, 0x50000, v146
	s_waitcnt vmcnt(12)
	v_pk_add_f32 v[126:127], v[126:127], v[184:185]
	v_pk_add_f32 v[128:129], v[128:129], v[186:187]
	v_pk_add_f32 v[122:123], v[122:123], v[188:189]
	v_pk_add_f32 v[124:125], v[124:125], v[190:191]
	v_pk_add_f32 v[118:119], v[118:119], v[192:193]
	v_pk_add_f32 v[120:121], v[120:121], v[194:195]
	v_pk_add_f32 v[114:115], v[114:115], v[198:199]
	v_pk_add_f32 v[116:117], v[116:117], v[200:201]
	global_store_dwordx4 v147, v[126:129], s[48:49]
	global_store_dwordx4 v147, v[122:125], s[48:49] offset:16
	global_store_dwordx4 v147, v[118:121], s[48:49] offset:512
	global_store_dwordx4 v147, v[114:117], s[48:49] offset:528
	v_mul_f32_e32 v149, v126, v126
	v_mul_f32_e32 v150, v127, v127
	v_fmac_f32_e32 v149, v128, v128
	v_fmac_f32_e32 v150, v129, v129
	v_fmac_f32_e32 v149, v122, v122
	v_fmac_f32_e32 v150, v123, v123
	v_fmac_f32_e32 v149, v124, v124
	v_fmac_f32_e32 v150, v125, v125
	v_fmac_f32_e32 v149, v118, v118
	v_fmac_f32_e32 v150, v119, v119
	v_fmac_f32_e32 v149, v120, v120
	v_fmac_f32_e32 v150, v121, v121
	v_fmac_f32_e32 v149, v114, v114
	v_fmac_f32_e32 v150, v115, v115
	v_fmac_f32_e32 v149, v116, v116
	v_fmac_f32_e32 v150, v117, v117
	s_cmp_lg_u32 s100, 0
	s_cbranch_scc1 .Lskiphb_l15_1
	v_pk_mul_f32 v[184:185], v[126:127], v[78:79]
	v_pk_mul_f32 v[186:187], v[128:129], v[80:81]
	v_pk_mul_f32 v[188:189], v[122:123], v[82:83]
	v_pk_mul_f32 v[190:191], v[124:125], v[84:85]
	v_pk_mul_f32 v[192:193], v[118:119], v[94:95]
	v_pk_mul_f32 v[194:195], v[120:121], v[96:97]
	v_pk_mul_f32 v[198:199], v[114:115], v[98:99]
	v_pk_mul_f32 v[200:201], v[116:117], v[100:101]
	v_cvt_pk_bf16_f32 v184, v184, v185
	v_cvt_pk_bf16_f32 v185, v186, v187
	v_cvt_pk_bf16_f32 v186, v188, v189
	v_cvt_pk_bf16_f32 v187, v190, v191
	v_cvt_pk_bf16_f32 v192, v192, v193
	v_cvt_pk_bf16_f32 v193, v194, v195
	v_cvt_pk_bf16_f32 v194, v198, v199
	v_cvt_pk_bf16_f32 v195, v200, v201
	global_store_dwordx4 v148, v[184:187], s[62:63]
	global_store_dwordx4 v148, v[192:195], s[62:63] offset:256
; DI void st8(bf16_t* p, f32x4 a, f32x4 b) { u32x4 w; w.x = pk2(a[0], a[1]); w.y = pk2(a[2], a[3]); w.z = pk2(b[0], b[1]); w.w = pk2(b[2], b[3]); *(u32x4*)p = w; }
;     DI void operator()(const AccT& acc, const Unit& u, int wr, int wc, int fr, int fq, const LAS float* rt) const {
;     ...
;                     for (int bj = 0; bj < 2; ++bj) { const size_t o = (size_t)row * DM + col0 + bj * HALF; bx[mm][bj][0] = *(const f32x4*)(base + o); bx[mm][bj][1] = *(const f32x4*)(base + o + 4); } }
;                 __builtin_amdgcn_sched_barrier(0);
; #pragma unroll
;                 for (int mm = 0; mm < 2; ++mm) { const int m = mh * 2 + mm; const int row = u.pm * BM + ai * HALF + wr * 64 + m * 16 + fr; float ss = 0.f;
; #pragma unroll
;                     for (int bj = 0; bj < 2; ++bj) { const size_t o = (size_t)row * DM + col0 + bj * HALF;
;                         const f32x4 x0 = bx[mm][bj][0] + acc[ai][bj][m][0], x1 = bx[mm][bj][1] + acc[ai][bj][m][1];
;                         *(f32x4*)(out + o) = x0; *(f32x4*)(out + o + 4) = x1;
;                         ss += (x0[0] * x0[0] + x0[1] * x0[1]) + (x0[2] * x0[2] + x0[3] * x0[3]) + (x1[0] * x1[0] + x1[1] * x1[1]) + (x1[2] * x1[2] + x1[3] * x1[3]);
;                         st8(hb + o, x0 * gv[bj][0], x1 * gv[bj][1]); }
.Lskiphb_l15_1:
	v_add_f32_e32 v126, v149, v150
	v_add_u32_e32 v147, 0x10000, v147
	v_add_u32_e32 v148, 0x8000, v148
	global_load_dwordx4 v[172:175], v146, s[30:31]
	global_load_dwordx4 v[188:191], v146, s[30:31] offset:16
	global_load_dwordx4 v[198:201], v146, s[30:31] offset:512
	global_load_dwordx4 v[122:125], v146, s[30:31] offset:528
	v_add_u32_e32 v146, 0x10000, v146
	global_load_dwordx4 v[118:121], v146, s[30:31]
	global_load_dwordx4 v[114:117], v146, s[30:31] offset:16
	global_load_dwordx4 v[184:187], v146, s[30:31] offset:512
	global_load_dwordx4 v[192:195], v146, s[30:31] offset:528
	v_add_u32_e32 v146, 0x10000, v146
	s_waitcnt vmcnt(16)
	v_pk_add_f32 v[110:111], v[110:111], v[204:205]
	v_pk_add_f32 v[112:113], v[112:113], v[206:207]
	v_pk_add_f32 v[106:107], v[106:107], v[208:209]
	v_pk_add_f32 v[108:109], v[108:109], v[210:211]
	v_pk_add_f32 v[102:103], v[102:103], v[158:159]
	v_pk_add_f32 v[104:105], v[104:105], v[160:161]
	v_pk_add_f32 v[90:91], v[90:91], v[176:177]
	v_pk_add_f32 v[92:93], v[92:93], v[178:179]
	global_store_dwordx4 v147, v[110:113], s[48:49]
	global_store_dwordx4 v147, v[106:109], s[48:49] offset:16
	global_store_dwordx4 v147, v[102:105], s[48:49] offset:512
	global_store_dwordx4 v147, v[90:93], s[48:49] offset:528
	v_mul_f32_e32 v149, v110, v110
	v_mul_f32_e32 v150, v111, v111
	v_fmac_f32_e32 v149, v112, v112
	v_fmac_f32_e32 v150, v113, v113
	v_fmac_f32_e32 v149, v106, v106
	v_fmac_f32_e32 v150, v107, v107
	v_fmac_f32_e32 v149, v108, v108
	v_fmac_f32_e32 v150, v109, v109
	v_fmac_f32_e32 v149, v102, v102
	v_fmac_f32_e32 v150, v103, v103
	v_fmac_f32_e32 v149, v104, v104
	v_fmac_f32_e32 v150, v105, v105
	v_fmac_f32_e32 v149, v90, v90
	v_fmac_f32_e32 v150, v91, v91
	v_fmac_f32_e32 v149, v92, v92
	v_fmac_f32_e32 v150, v93, v93
	s_cmp_lg_u32 s100, 0
	s_cbranch_scc1 .Lskiphb_l15_2
	v_pk_mul_f32 v[204:205], v[110:111], v[78:79]
	v_pk_mul_f32 v[206:207], v[112:113], v[80:81]
	v_pk_mul_f32 v[208:209], v[106:107], v[82:83]
	v_pk_mul_f32 v[210:211], v[108:109], v[84:85]
	v_pk_mul_f32 v[158:159], v[102:103], v[94:95]
	v_pk_mul_f32 v[160:161], v[104:105], v[96:97]
	v_pk_mul_f32 v[176:177], v[90:91], v[98:99]
	v_pk_mul_f32 v[178:179], v[92:93], v[100:101]
	v_cvt_pk_bf16_f32 v204, v204, v205
	v_cvt_pk_bf16_f32 v205, v206, v207
	v_cvt_pk_bf16_f32 v206, v208, v209
	v_cvt_pk_bf16_f32 v207, v210, v211
	v_cvt_pk_bf16_f32 v158, v158, v159
	v_cvt_pk_bf16_f32 v159, v160, v161
	v_cvt_pk_bf16_f32 v160, v176, v177
	v_cvt_pk_bf16_f32 v161, v178, v179
	global_store_dwordx4 v148, v[204:207], s[62:63]
	global_store_dwordx4 v148, v[158:161], s[62:63] offset:256
.Lskiphb_l15_2:
	v_add_f32_e32 v110, v149, v150
	v_add_u32_e32 v147, 0x10000, v147
	v_add_u32_e32 v148, 0x8000, v148
	global_load_dwordx4 v[208:211], v146, s[30:31]
	global_load_dwordx4 v[176:179], v146, s[30:31] offset:16
	global_load_dwordx4 v[106:109], v146, s[30:31] offset:512
	global_load_dwordx4 v[102:105], v146, s[30:31] offset:528
	v_add_u32_e32 v146, 0x10000, v146
	s_waitcnt vmcnt(20)
	v_pk_add_f32 v[86:87], v[86:87], v[138:139]
	v_pk_add_f32 v[88:89], v[88:89], v[140:141]
	v_pk_add_f32 v[74:75], v[74:75], v[134:135]
	v_pk_add_f32 v[76:77], v[76:77], v[136:137]
	v_pk_add_f32 v[70:71], v[70:71], v[130:131]
	v_pk_add_f32 v[72:73], v[72:73], v[132:133]
	v_pk_add_f32 v[66:67], v[66:67], v[154:155]
	v_pk_add_f32 v[68:69], v[68:69], v[156:157]
	global_store_dwordx4 v147, v[86:89], s[48:49]
	global_store_dwordx4 v147, v[74:77], s[48:49] offset:16
	global_store_dwordx4 v147, v[70:73], s[48:49] offset:512
	global_store_dwordx4 v147, v[66:69], s[48:49] offset:528
	v_mul_f32_e32 v149, v86, v86
	v_mul_f32_e32 v150, v87, v87
	v_fmac_f32_e32 v149, v88, v88
	v_fmac_f32_e32 v150, v89, v89
	v_fmac_f32_e32 v149, v74, v74
	v_fmac_f32_e32 v150, v75, v75
	v_fmac_f32_e32 v149, v76, v76
	v_fmac_f32_e32 v150, v77, v77
	v_fmac_f32_e32 v149, v70, v70
	v_fmac_f32_e32 v150, v71, v71
	v_fmac_f32_e32 v149, v72, v72
	v_fmac_f32_e32 v150, v73, v73
	v_fmac_f32_e32 v149, v66, v66
	v_fmac_f32_e32 v150, v67, v67
	v_fmac_f32_e32 v149, v68, v68
	v_fmac_f32_e32 v150, v69, v69
	s_cmp_lg_u32 s100, 0
	s_cbranch_scc1 .Lskiphb_l15_3
	v_pk_mul_f32 v[138:139], v[86:87], v[78:79]
	v_pk_mul_f32 v[140:141], v[88:89], v[80:81]
	v_pk_mul_f32 v[134:135], v[74:75], v[82:83]
	v_pk_mul_f32 v[136:137], v[76:77], v[84:85]
	v_pk_mul_f32 v[130:131], v[70:71], v[94:95]
	v_pk_mul_f32 v[132:133], v[72:73], v[96:97]
	v_pk_mul_f32 v[154:155], v[66:67], v[98:99]
	v_pk_mul_f32 v[156:157], v[68:69], v[100:101]
	v_cvt_pk_bf16_f32 v138, v138, v139
	v_cvt_pk_bf16_f32 v139, v140, v141
	v_cvt_pk_bf16_f32 v140, v134, v135
	v_cvt_pk_bf16_f32 v141, v136, v137
	v_cvt_pk_bf16_f32 v130, v130, v131
	v_cvt_pk_bf16_f32 v131, v132, v133
	v_cvt_pk_bf16_f32 v132, v154, v155
	v_cvt_pk_bf16_f32 v133, v156, v157
	global_store_dwordx4 v148, v[138:141], s[62:63]
	global_store_dwordx4 v148, v[130:133], s[62:63] offset:256
; DI void st8(bf16_t* p, f32x4 a, f32x4 b) { u32x4 w; w.x = pk2(a[0], a[1]); w.y = pk2(a[2], a[3]); w.z = pk2(b[0], b[1]); w.w = pk2(b[2], b[3]); *(u32x4*)p = w; }
;     DI void operator()(const AccT& acc, const Unit& u, int wr, int wc, int fr, int fq, const LAS float* rt) const {
;     ...
;                     for (int bj = 0; bj < 2; ++bj) { const size_t o = (size_t)row * DM + col0 + bj * HALF; bx[mm][bj][0] = *(const f32x4*)(base + o); bx[mm][bj][1] = *(const f32x4*)(base + o + 4); } }
;                 __builtin_amdgcn_sched_barrier(0);
; #pragma unroll
;                 for (int mm = 0; mm < 2; ++mm) { const int m = mh * 2 + mm; const int row = u.pm * BM + ai * HALF + wr * 64 + m * 16 + fr; float ss = 0.f;
; #pragma unroll
;                     for (int bj = 0; bj < 2; ++bj) { const size_t o = (size_t)row * DM + col0 + bj * HALF;
;                         const f32x4 x0 = bx[mm][bj][0] + acc[ai][bj][m][0], x1 = bx[mm][bj][1] + acc[ai][bj][m][1];
;                         *(f32x4*)(out + o) = x0; *(f32x4*)(out + o + 4) = x1;
;                         ss += (x0[0] * x0[0] + x0[1] * x0[1]) + (x0[2] * x0[2] + x0[3] * x0[3]) + (x1[0] * x1[0] + x1[1] * x1[1]) + (x1[2] * x1[2] + x1[3] * x1[3]);
;                         st8(hb + o, x0 * gv[bj][0], x1 * gv[bj][1]); }
.Lskiphb_l15_3:
	v_add_f32_e32 v86, v149, v150
	v_add_u32_e32 v147, 0x50000, v147
	v_add_u32_e32 v148, 0x28000, v148
	global_load_dwordx4 v[90:93], v146, s[30:31]
	global_load_dwordx4 v[204:207], v146, s[30:31] offset:16
	global_load_dwordx4 v[158:161], v146, s[30:31] offset:512
	global_load_dwordx4 v[134:137], v146, s[30:31] offset:528
	s_waitcnt vmcnt(20)
	v_pk_add_f32 v[62:63], v[62:63], v[172:173]
	v_pk_add_f32 v[64:65], v[64:65], v[174:175]
	v_pk_add_f32 v[58:59], v[58:59], v[188:189]
	v_pk_add_f32 v[60:61], v[60:61], v[190:191]
	v_pk_add_f32 v[54:55], v[54:55], v[198:199]
	v_pk_add_f32 v[56:57], v[56:57], v[200:201]
	v_pk_add_f32 v[50:51], v[50:51], v[122:123]
	v_pk_add_f32 v[52:53], v[52:53], v[124:125]
	global_store_dwordx4 v147, v[62:65], s[48:49]
	global_store_dwordx4 v147, v[58:61], s[48:49] offset:16
	global_store_dwordx4 v147, v[54:57], s[48:49] offset:512
	global_store_dwordx4 v147, v[50:53], s[48:49] offset:528
	v_mul_f32_e32 v149, v62, v62
	v_mul_f32_e32 v150, v63, v63
	v_fmac_f32_e32 v149, v64, v64
	v_fmac_f32_e32 v150, v65, v65
	v_fmac_f32_e32 v149, v58, v58
	v_fmac_f32_e32 v150, v59, v59
	v_fmac_f32_e32 v149, v60, v60
	v_fmac_f32_e32 v150, v61, v61
	v_fmac_f32_e32 v149, v54, v54
	v_fmac_f32_e32 v150, v55, v55
	v_fmac_f32_e32 v149, v56, v56
	v_fmac_f32_e32 v150, v57, v57
	v_fmac_f32_e32 v149, v50, v50
	v_fmac_f32_e32 v150, v51, v51
	v_fmac_f32_e32 v149, v52, v52
	v_fmac_f32_e32 v150, v53, v53
	s_cmp_lg_u32 s100, 0
	s_cbranch_scc1 .Lskiphb_l15_4
	v_pk_mul_f32 v[172:173], v[62:63], v[78:79]
	v_pk_mul_f32 v[174:175], v[64:65], v[80:81]
	v_pk_mul_f32 v[188:189], v[58:59], v[82:83]
	v_pk_mul_f32 v[190:191], v[60:61], v[84:85]
	v_pk_mul_f32 v[198:199], v[54:55], v[94:95]
	v_pk_mul_f32 v[200:201], v[56:57], v[96:97]
	v_pk_mul_f32 v[122:123], v[50:51], v[98:99]
	v_pk_mul_f32 v[124:125], v[52:53], v[100:101]
	v_cvt_pk_bf16_f32 v172, v172, v173
	v_cvt_pk_bf16_f32 v173, v174, v175
	v_cvt_pk_bf16_f32 v174, v188, v189
	v_cvt_pk_bf16_f32 v175, v190, v191
	v_cvt_pk_bf16_f32 v198, v198, v199
	v_cvt_pk_bf16_f32 v199, v200, v201
	v_cvt_pk_bf16_f32 v200, v122, v123
	v_cvt_pk_bf16_f32 v201, v124, v125
	global_store_dwordx4 v148, v[172:175], s[62:63]
	global_store_dwordx4 v148, v[198:201], s[62:63] offset:256
.Lskiphb_l15_4:
	v_add_f32_e32 v62, v149, v150
	v_add_u32_e32 v147, 0x10000, v147
	v_add_u32_e32 v148, 0x8000, v148
	s_waitcnt vmcnt(20)
	v_pk_add_f32 v[46:47], v[46:47], v[118:119]
	v_pk_add_f32 v[48:49], v[48:49], v[120:121]
	v_pk_add_f32 v[42:43], v[42:43], v[114:115]
	v_pk_add_f32 v[44:45], v[44:45], v[116:117]
	v_pk_add_f32 v[38:39], v[38:39], v[184:185]
	v_pk_add_f32 v[40:41], v[40:41], v[186:187]
	v_pk_add_f32 v[34:35], v[34:35], v[192:193]
	v_pk_add_f32 v[36:37], v[36:37], v[194:195]
	global_store_dwordx4 v147, v[46:49], s[48:49]
	global_store_dwordx4 v147, v[42:45], s[48:49] offset:16
	global_store_dwordx4 v147, v[38:41], s[48:49] offset:512
	global_store_dwordx4 v147, v[34:37], s[48:49] offset:528
	v_mul_f32_e32 v149, v46, v46
	v_mul_f32_e32 v150, v47, v47
	v_fmac_f32_e32 v149, v48, v48
	v_fmac_f32_e32 v150, v49, v49
	v_fmac_f32_e32 v149, v42, v42
	v_fmac_f32_e32 v150, v43, v43
	v_fmac_f32_e32 v149, v44, v44
	v_fmac_f32_e32 v150, v45, v45
	v_fmac_f32_e32 v149, v38, v38
	v_fmac_f32_e32 v150, v39, v39
	v_fmac_f32_e32 v149, v40, v40
	v_fmac_f32_e32 v150, v41, v41
	v_fmac_f32_e32 v149, v34, v34
	v_fmac_f32_e32 v150, v35, v35
	v_fmac_f32_e32 v149, v36, v36
	v_fmac_f32_e32 v150, v37, v37
	s_cmp_lg_u32 s100, 0
	s_cbranch_scc1 .Lskiphb_l15_5
	v_pk_mul_f32 v[118:119], v[46:47], v[78:79]
	v_pk_mul_f32 v[120:121], v[48:49], v[80:81]
	v_pk_mul_f32 v[114:115], v[42:43], v[82:83]
	v_pk_mul_f32 v[116:117], v[44:45], v[84:85]
	v_pk_mul_f32 v[184:185], v[38:39], v[94:95]
	v_pk_mul_f32 v[186:187], v[40:41], v[96:97]
	v_pk_mul_f32 v[192:193], v[34:35], v[98:99]
	v_pk_mul_f32 v[194:195], v[36:37], v[100:101]
	v_cvt_pk_bf16_f32 v118, v118, v119
	v_cvt_pk_bf16_f32 v119, v120, v121
	v_cvt_pk_bf16_f32 v120, v114, v115
	v_cvt_pk_bf16_f32 v121, v116, v117
	v_cvt_pk_bf16_f32 v184, v184, v185
	v_cvt_pk_bf16_f32 v185, v186, v187
	v_cvt_pk_bf16_f32 v186, v192, v193
	v_cvt_pk_bf16_f32 v187, v194, v195
	global_store_dwordx4 v148, v[118:121], s[62:63]
	global_store_dwordx4 v148, v[184:187], s[62:63] offset:256
; DI void st8(bf16_t* p, f32x4 a, f32x4 b) { u32x4 w; w.x = pk2(a[0], a[1]); w.y = pk2(a[2], a[3]); w.z = pk2(b[0], b[1]); w.w = pk2(b[2], b[3]); *(u32x4*)p = w; }
;     DI void operator()(const AccT& acc, const Unit& u, int wr, int wc, int fr, int fq, const LAS float* rt) const {
;     ...
;                     for (int bj = 0; bj < 2; ++bj) { const size_t o = (size_t)row * DM + col0 + bj * HALF; bx[mm][bj][0] = *(const f32x4*)(base + o); bx[mm][bj][1] = *(const f32x4*)(base + o + 4); } }
;                 __builtin_amdgcn_sched_barrier(0);
; #pragma unroll
;                 for (int mm = 0; mm < 2; ++mm) { const int m = mh * 2 + mm; const int row = u.pm * BM + ai * HALF + wr * 64 + m * 16 + fr; float ss = 0.f;
; #pragma unroll
;                     for (int bj = 0; bj < 2; ++bj) { const size_t o = (size_t)row * DM + col0 + bj * HALF;
;                         const f32x4 x0 = bx[mm][bj][0] + acc[ai][bj][m][0], x1 = bx[mm][bj][1] + acc[ai][bj][m][1];
;                         *(f32x4*)(out + o) = x0; *(f32x4*)(out + o + 4) = x1;
;                         ss += (x0[0] * x0[0] + x0[1] * x0[1]) + (x0[2] * x0[2] + x0[3] * x0[3]) + (x1[0] * x1[0] + x1[1] * x1[1]) + (x1[2] * x1[2] + x1[3] * x1[3]);
;                         st8(hb + o, x0 * gv[bj][0], x1 * gv[bj][1]); }
;                     ss += __shfl_xor(ss, 16); ss += __shfl_xor(ss, 32);
;                     if (fq == 0) part[(size_t)row * 16 + u.pn * 4 + wc] = ss; }
.Lskiphb_l15_5:
	v_add_f32_e32 v46, v149, v150
	v_add_u32_e32 v147, 0x10000, v147
	v_add_u32_e32 v148, 0x8000, v148
	s_waitcnt vmcnt(16)
	v_pk_add_f32 v[30:31], v[30:31], v[208:209]
	v_pk_add_f32 v[32:33], v[32:33], v[210:211]
	v_pk_add_f32 v[26:27], v[26:27], v[176:177]
	v_pk_add_f32 v[28:29], v[28:29], v[178:179]
	v_pk_add_f32 v[22:23], v[22:23], v[106:107]
	v_pk_add_f32 v[24:25], v[24:25], v[108:109]
	v_pk_add_f32 v[18:19], v[18:19], v[102:103]
	v_pk_add_f32 v[20:21], v[20:21], v[104:105]
	global_store_dwordx4 v147, v[30:33], s[48:49]
	global_store_dwordx4 v147, v[26:29], s[48:49] offset:16
	global_store_dwordx4 v147, v[22:25], s[48:49] offset:512
	global_store_dwordx4 v147, v[18:21], s[48:49] offset:528
	v_mul_f32_e32 v149, v30, v30
	v_mul_f32_e32 v150, v31, v31
	v_fmac_f32_e32 v149, v32, v32
	v_fmac_f32_e32 v150, v33, v33
	v_fmac_f32_e32 v149, v26, v26
	v_fmac_f32_e32 v150, v27, v27
	v_fmac_f32_e32 v149, v28, v28
	v_fmac_f32_e32 v150, v29, v29
	v_fmac_f32_e32 v149, v22, v22
	v_fmac_f32_e32 v150, v23, v23
	v_fmac_f32_e32 v149, v24, v24
	v_fmac_f32_e32 v150, v25, v25
	v_fmac_f32_e32 v149, v18, v18
	v_fmac_f32_e32 v150, v19, v19
	v_fmac_f32_e32 v149, v20, v20
	v_fmac_f32_e32 v150, v21, v21
	s_cmp_lg_u32 s100, 0
	s_cbranch_scc1 .Lskiphb_l15_6
	v_pk_mul_f32 v[208:209], v[30:31], v[78:79]
	v_pk_mul_f32 v[210:211], v[32:33], v[80:81]
	v_pk_mul_f32 v[176:177], v[26:27], v[82:83]
	v_pk_mul_f32 v[178:179], v[28:29], v[84:85]
	v_pk_mul_f32 v[106:107], v[22:23], v[94:95]
	v_pk_mul_f32 v[108:109], v[24:25], v[96:97]
	v_pk_mul_f32 v[102:103], v[18:19], v[98:99]
	v_pk_mul_f32 v[104:105], v[20:21], v[100:101]
	v_cvt_pk_bf16_f32 v208, v208, v209
	v_cvt_pk_bf16_f32 v209, v210, v211
	v_cvt_pk_bf16_f32 v210, v176, v177
	v_cvt_pk_bf16_f32 v211, v178, v179
	v_cvt_pk_bf16_f32 v106, v106, v107
	v_cvt_pk_bf16_f32 v107, v108, v109
	v_cvt_pk_bf16_f32 v108, v102, v103
	v_cvt_pk_bf16_f32 v109, v104, v105
	global_store_dwordx4 v148, v[208:211], s[62:63]
	global_store_dwordx4 v148, v[106:109], s[62:63] offset:256
.Lskiphb_l15_6:
	v_add_f32_e32 v30, v149, v150
	v_add_u32_e32 v147, 0x10000, v147
	v_add_u32_e32 v148, 0x8000, v148
	s_waitcnt vmcnt(12)
	v_pk_add_f32 v[14:15], v[14:15], v[90:91]
	v_pk_add_f32 v[16:17], v[16:17], v[92:93]
	v_pk_add_f32 v[10:11], v[10:11], v[204:205]
	v_pk_add_f32 v[12:13], v[12:13], v[206:207]
	v_pk_add_f32 v[6:7], v[6:7], v[158:159]
	v_pk_add_f32 v[8:9], v[8:9], v[160:161]
	v_pk_add_f32 v[2:3], v[2:3], v[134:135]
	v_pk_add_f32 v[4:5], v[4:5], v[136:137]
	global_store_dwordx4 v147, v[14:17], s[48:49]
	global_store_dwordx4 v147, v[10:13], s[48:49] offset:16
	global_store_dwordx4 v147, v[6:9], s[48:49] offset:512
	global_store_dwordx4 v147, v[2:5], s[48:49] offset:528
	v_mul_f32_e32 v149, v14, v14
	v_mul_f32_e32 v150, v15, v15
	v_fmac_f32_e32 v149, v16, v16
	v_fmac_f32_e32 v150, v17, v17
	v_fmac_f32_e32 v149, v10, v10
	v_fmac_f32_e32 v150, v11, v11
	v_fmac_f32_e32 v149, v12, v12
	v_fmac_f32_e32 v150, v13, v13
	v_fmac_f32_e32 v149, v6, v6
	v_fmac_f32_e32 v150, v7, v7
	v_fmac_f32_e32 v149, v8, v8
	v_fmac_f32_e32 v150, v9, v9
	v_fmac_f32_e32 v149, v2, v2
	v_fmac_f32_e32 v150, v3, v3
	v_fmac_f32_e32 v149, v4, v4
	v_fmac_f32_e32 v150, v5, v5
	s_cmp_lg_u32 s100, 0
	s_cbranch_scc1 .Lskiphb_l15_7
	v_pk_mul_f32 v[90:91], v[14:15], v[78:79]
	v_pk_mul_f32 v[92:93], v[16:17], v[80:81]
	v_pk_mul_f32 v[204:205], v[10:11], v[82:83]
	v_pk_mul_f32 v[206:207], v[12:13], v[84:85]
	v_pk_mul_f32 v[158:159], v[6:7], v[94:95]
	v_pk_mul_f32 v[160:161], v[8:9], v[96:97]
	v_pk_mul_f32 v[134:135], v[2:3], v[98:99]
	v_pk_mul_f32 v[136:137], v[4:5], v[100:101]
	v_cvt_pk_bf16_f32 v90, v90, v91
	v_cvt_pk_bf16_f32 v91, v92, v93
	v_cvt_pk_bf16_f32 v92, v204, v205
	v_cvt_pk_bf16_f32 v93, v206, v207
	v_cvt_pk_bf16_f32 v158, v158, v159
	v_cvt_pk_bf16_f32 v159, v160, v161
	v_cvt_pk_bf16_f32 v160, v134, v135
	v_cvt_pk_bf16_f32 v161, v136, v137
	global_store_dwordx4 v148, v[90:93], s[62:63]
	global_store_dwordx4 v148, v[158:161], s[62:63] offset:256
.Lskiphb_l15_7:
	v_add_f32_e32 v14, v149, v150
	v_lshrrev_b32_e32 v152, 5, v182
	v_lshlrev_b32_e32 v152, 2, v152
	v_lshl_add_u32 v70, v151, 6, v152
	v_mov_b32_e32 v153, s78
	v_lshl_add_u32 v70, v153, 4, v70
	v_add_u32_e32 v71, 0x2000, v70
	v_mbcnt_lo_u32_b32 v72, -1, 0
	v_mbcnt_hi_u32_b32 v72, -1, v72
	v_xor_b32_e32 v73, 32, v72
	v_xor_b32_e32 v72, 16, v72
	v_lshlrev_b32_e32 v73, 2, v73
	v_lshlrev_b32_e32 v72, 2, v72
	ds_bpermute_b32 v154, v72, v142
	ds_bpermute_b32 v155, v72, v126
	ds_bpermute_b32 v156, v72, v110
	ds_bpermute_b32 v157, v72, v86
	ds_bpermute_b32 v74, v72, v62
	ds_bpermute_b32 v75, v72, v46
	ds_bpermute_b32 v76, v72, v30
	ds_bpermute_b32 v77, v72, v14
	s_waitcnt lgkmcnt(0)
	v_add_f32_e32 v142, v142, v154
	v_add_f32_e32 v126, v126, v155
	v_add_f32_e32 v110, v110, v156
	v_add_f32_e32 v86, v86, v157
	v_add_f32_e32 v62, v62, v74
	v_add_f32_e32 v46, v46, v75
	v_add_f32_e32 v30, v30, v76
	v_add_f32_e32 v14, v14, v77
	ds_bpermute_b32 v154, v73, v142
	ds_bpermute_b32 v155, v73, v126
	ds_bpermute_b32 v156, v73, v110
	ds_bpermute_b32 v157, v73, v86
	ds_bpermute_b32 v74, v73, v62
	ds_bpermute_b32 v75, v73, v46
	ds_bpermute_b32 v76, v73, v30
	ds_bpermute_b32 v77, v73, v14
	s_waitcnt lgkmcnt(0)
	v_add_f32_e32 v142, v142, v154
	v_add_f32_e32 v126, v126, v155
	v_add_f32_e32 v110, v110, v156
	v_add_f32_e32 v86, v86, v157
	v_add_f32_e32 v62, v62, v74
	v_add_f32_e32 v46, v46, v75
	v_add_f32_e32 v30, v30, v76
	v_add_f32_e32 v14, v14, v77
	s_mov_b64 exec, 0xffff
	global_store_dword v70, v142, s[66:67]
	global_store_dword v70, v126, s[66:67] offset:1024
	global_store_dword v70, v110, s[66:67] offset:2048
	global_store_dword v70, v86, s[66:67] offset:3072
	global_store_dword v71, v62, s[66:67]
	global_store_dword v71, v46, s[66:67] offset:1024
	global_store_dword v71, v30, s[66:67] offset:2048
	global_store_dword v71, v14, s[66:67] offset:3072
	s_mov_b64 exec, -1
	s_lshl_b32 s44, s78, 2
	s_ashr_i32 s45, s44, 31
	s_lshl_b32 s28, s81, 2
	s_andn2_b64 vcc, exec, s[92:93]
	s_mov_b64 s[36:37], -1
	s_cbranch_vccnz .LBB0_1432
	s_andn2_b64 vcc, exec, s[52:53]
	s_cbranch_vccnz .LBB0_1431
	s_barrier
	s_branch .LBB0_1431
